# phase F: RA/DB scale slices staged to spare LDS by LDS-DMA in the last K-iteration; SwiGLU epilogue reads them from LDS, no vmcnt drain
# speedup vs baseline: 1.0003x; 1.0003x over previous
; #define PG8_WAIT_V(n) asm volatile("s_waitcnt vmcnt(" #n ")" ::: "memory")
;     __device__ __forceinline__ void operator()(const i32x4 (&acc)[2][2][4][2], const Unit& u, int wr, int wc, int fr, int fq) const {
;         const int row0 = u.pm * BM + wr * 64 + fr, col0 = u.pn * HALF + wc * 32 + 8 * fq, brow = u.pn * BM + wc * 32 + 8 * fq;
;         const f32x4 dg0 = *(const f32x4*)(DB + brow), dg1 = *(const f32x4*)(DB + brow + 4), du0 = *(const f32x4*)(DB + brow + HALF), du1 = *(const f32x4*)(DB + brow + HALF + 4);
;         float rav[2][4];
; #pragma unroll
;         for (int ai = 0; ai < 2; ++ai)
; #pragma unroll
;             for (int m = 0; m < 4; ++m) rav[ai][m] = RA[row0 + ai * HALF + m * 16];
; template <class Epi, class Sched, bool ALIGN_EPI = false, bool SP2 = false, bool I8 = false>
; __device__ __forceinline__ void gemm_phase(PG8_LAS unsigned char* lds, const Gemm g, const Sched& S, const Epi& E) {
;     ...
;         for (int t = 0; t < nt; t += 2) {
;             const bool last = (t == nt - 2);
;             const char* a1 = cA + (size_t)(t + 1) * kstep;
;             const char* a2 = last ? nA : cA + (size_t)(t + 2) * kstep; const char* b2 = last ? nB : cB + (size_t)(t + 2) * kstep;
;             const char* a3 = a2 + kstep; const char* b3 = b2 + kstep;
;             if (last && has_next) S.a_ready(nxt);
;             if constexpr (SP2) {
;             PG8_LDB(B0, 0, 0); PG8_LDB(B1, 0, 1); PG8_SCHED; PG8_LDA(At, 0, 0); PG8_STAGE(PG8_SA(1, 1), a1 + hstep, voffA);
;             PG8_WAIT_V(8); PG8_WAIT_L(0); PG8_BAR; PG8_MMA(0, 0, At, B0); PG8_MMA(0, 1, At, B1); PG8_BAR; PG8_SCHED;
;             PG8_LDA(At, 0, 1); PG8_STAGE(PG8_SB(0, 0), b2, voffB); PG8_STAGE(PG8_SB(0, 1), b2 + hstep, voffB); PG8_STAGE(PG8_SA(0, 0), a2, voffA);
;             PG8_WAIT_V(8); PG8_WAIT_L(0); PG8_BAR; PG8_MMA(1, 0, At, B0); PG8_MMA(1, 1, At, B1); PG8_BAR; PG8_SCHED;
;             PG8_LDB(B0, 1, 0); PG8_LDB(B1, 1, 1); PG8_SCHED; PG8_LDA(At, 1, 0); PG8_STAGE(PG8_SA(0, 1), a2 + hstep, voffA);
;             PG8_WAIT_V(8); PG8_WAIT_L(0); PG8_BAR; PG8_MMA(0, 0, At, B0); PG8_MMA(0, 1, At, B1); PG8_BAR; PG8_SCHED;
;             PG8_LDA(At, 1, 1); PG8_STAGE(PG8_SB(1, 0), b3, voffB); PG8_STAGE(PG8_SB(1, 1), b3 + hstep, voffB); PG8_STAGE(PG8_SA(1, 0), a3, voffA);
;             PG8_WAIT_V(8); PG8_WAIT_L(0); PG8_BAR; PG8_MMA(1, 0, At, B0); PG8_MMA(1, 1, At, B1); PG8_BAR; PG8_SCHED;
.LBB0_1591:
	s_add_u32 s44, s40, 0xfff80080
	s_addc_u32 s45, s41, -1
	s_add_i32 s64, 0, 0x10000
	s_cmp_eq_u32 s61, 28
	s_cselect_b32 s49, s25, s45
	s_cselect_b32 s48, s57, s44
	s_cselect_b32 s45, s23, s60
	s_cselect_b32 s44, s58, s59
	s_cbranch_scc0 .Lnoepf_F
	s_lshl_b32 s72, s34, 10
	s_add_u32 s72, s18, s72
	s_addc_u32 s73, s19, 0
	s_lshl_b32 s76, s35, 10
	s_add_u32 s76, s16, s76
	s_addc_u32 s77, s17, 0
	v_and_b32_e32 v239, 63, v0
	v_lshlrev_b32_e32 v239, 4, v239
	s_mov_b32 m0, 0x23800
	s_nop 0
	global_load_lds_dwordx4 v239, s[72:73]
	s_mov_b32 m0, 0x23c00
	s_nop 0
	global_load_lds_dwordx4 v239, s[76:77]
.Lnoepf_F:
	s_add_i32 s67, 0, 0x14000
	v_add_u32_e32 v144, s64, v167
	v_add_u32_e32 v158, s67, v167
	ds_read_b128 v[36:39], v144
	ds_read_b128 v[44:47], v144 offset:1024
	ds_read_b128 v[140:143], v144 offset:2048
	ds_read_b128 v[144:147], v144 offset:3072
	ds_read_b128 v[160:163], v158
	ds_read_b128 v[172:175], v158 offset:1024
	ds_read_b128 v[176:179], v158 offset:2048
	ds_read_b128 v[180:183], v158 offset:3072
	v_lshl_add_u64 v[164:165], s[40:41], 0, v[154:155]
	s_add_i32 m0, s50, 0xc000
	ds_read_b128 v[184:187], v171
	ds_read_b128 v[188:191], v171 offset:1024
	ds_read_b128 v[204:207], v171 offset:2048
	ds_read_b128 v[208:211], v171 offset:3072
	ds_read_b128 v[212:215], v171 offset:4096
	ds_read_b128 v[216:219], v171 offset:5120
	ds_read_b128 v[220:223], v171 offset:6144
	ds_read_b128 v[224:227], v171 offset:7168
	global_load_lds_dwordx4 v[164:165], off
	v_lshl_add_u64 v[164:165], s[40:41], 0, v[156:157]
	s_add_i32 m0, s50, 0xe000
	s_nop 0
	global_load_lds_dwordx4 v[164:165], off
	s_waitcnt vmcnt(8)
	s_waitcnt lgkmcnt(0)
	s_barrier
	s_setprio 1
	s_waitcnt lgkmcnt(0)
	v_mfma_i32_16x16x64_i8 v[136:139], v[36:39], v[184:187], v[136:139]
	v_mfma_i32_16x16x64_i8 v[128:131], v[140:143], v[184:187], v[128:131]
	v_mfma_i32_16x16x64_i8 v[120:123], v[36:39], v[204:207], v[120:123]
	v_mfma_i32_16x16x64_i8 v[112:115], v[140:143], v[204:207], v[112:115]
	v_mfma_i32_16x16x64_i8 v[104:107], v[36:39], v[212:215], v[104:107]
	v_mfma_i32_16x16x64_i8 v[96:99], v[140:143], v[212:215], v[96:99]
	v_mfma_i32_16x16x64_i8 v[88:91], v[36:39], v[220:223], v[88:91]
	v_mfma_i32_16x16x64_i8 v[80:83], v[140:143], v[220:223], v[80:83]
	v_mfma_i32_16x16x64_i8 v[136:139], v[44:47], v[188:191], v[136:139]
	v_mfma_i32_16x16x64_i8 v[128:131], v[144:147], v[188:191], v[128:131]
	v_mfma_i32_16x16x64_i8 v[120:123], v[44:47], v[208:211], v[120:123]
	v_mfma_i32_16x16x64_i8 v[112:115], v[144:147], v[208:211], v[112:115]
	v_mfma_i32_16x16x64_i8 v[104:107], v[44:47], v[216:219], v[104:107]
	v_mfma_i32_16x16x64_i8 v[96:99], v[144:147], v[216:219], v[96:99]
	v_mfma_i32_16x16x64_i8 v[88:91], v[44:47], v[224:227], v[88:91]
	v_mfma_i32_16x16x64_i8 v[80:83], v[144:147], v[224:227], v[80:83]
	s_setprio 0
	s_setprio 1
	v_mfma_i32_16x16x64_i8 v[132:135], v[160:163], v[184:187], v[132:135]
	v_mfma_i32_16x16x64_i8 v[124:127], v[176:179], v[184:187], v[124:127]
	v_mfma_i32_16x16x64_i8 v[116:119], v[160:163], v[204:207], v[116:119]
	v_mfma_i32_16x16x64_i8 v[108:111], v[176:179], v[204:207], v[108:111]
	v_mfma_i32_16x16x64_i8 v[100:103], v[160:163], v[212:215], v[100:103]
	v_mfma_i32_16x16x64_i8 v[92:95], v[176:179], v[212:215], v[92:95]
	v_mfma_i32_16x16x64_i8 v[84:87], v[160:163], v[220:223], v[84:87]
	v_mfma_i32_16x16x64_i8 v[76:79], v[176:179], v[220:223], v[76:79]
	v_mfma_i32_16x16x64_i8 v[132:135], v[172:175], v[188:191], v[132:135]
	v_mfma_i32_16x16x64_i8 v[124:127], v[180:183], v[188:191], v[124:127]
	v_mfma_i32_16x16x64_i8 v[116:119], v[172:175], v[208:211], v[116:119]
	v_mfma_i32_16x16x64_i8 v[108:111], v[180:183], v[208:211], v[108:111]
	v_mfma_i32_16x16x64_i8 v[100:103], v[172:175], v[216:219], v[100:103]
	v_mfma_i32_16x16x64_i8 v[92:95], v[180:183], v[216:219], v[92:95]
	v_mfma_i32_16x16x64_i8 v[84:87], v[172:175], v[224:227], v[84:87]
	v_mfma_i32_16x16x64_i8 v[76:79], v[180:183], v[224:227], v[76:79]
	s_setprio 0
	s_barrier
	s_add_i32 s64, s64, s47
	v_lshl_add_u64 v[164:165], s[44:45], 0, v[2:3]
	s_mov_b32 m0, s64
	ds_read_b128 v[184:187], v171 offset:16384
	ds_read_b128 v[188:191], v171 offset:17408
	ds_read_b128 v[204:207], v171 offset:18432
	ds_read_b128 v[208:211], v171 offset:19456
	ds_read_b128 v[212:215], v171 offset:20480
	ds_read_b128 v[216:219], v171 offset:21504
	ds_read_b128 v[220:223], v171 offset:22528
	ds_read_b128 v[224:227], v171 offset:23552
	global_load_lds_dwordx4 v[164:165], off
	s_add_i32 m0, s64, 0x2000
	s_add_u32 s64, s44, 0x80000
	v_lshl_add_u64 v[228:229], s[44:45], 0, v[148:149]
	s_addc_u32 s65, s45, 0
	s_add_i32 s67, s67, s47
	global_load_lds_dwordx4 v[228:229], off
	v_lshl_add_u64 v[240:241], s[64:65], 0, v[2:3]
	s_mov_b32 m0, s67
	v_lshl_add_u64 v[242:243], s[48:49], 0, v[150:151]
	global_load_lds_dwordx4 v[240:241], off
	v_lshl_add_u64 v[240:241], s[64:65], 0, v[148:149]
	s_add_i32 m0, s67, 0x2000
	s_nop 0
	global_load_lds_dwordx4 v[240:241], off
	v_lshl_add_u64 v[240:241], s[48:49], 0, v[152:153]
	s_mov_b32 m0, s50
	s_nop 0
	global_load_lds_dwordx4 v[240:241], off
	s_mov_b32 m0, s51
	s_nop 0
	global_load_lds_dwordx4 v[242:243], off
	s_waitcnt vmcnt(8)
	s_waitcnt lgkmcnt(0)
	s_barrier
; #define PG8_STAGE(bufoff, gbase, voff) do { _Pragma("unroll") for (int _i = 0; _i < 2; ++_i) \
;         __builtin_amdgcn_global_load_lds((const unsigned*)((const char*)(gbase) + (voff)[_i]), (PG8_LAS unsigned*)(lds + (bufoff) + ldsw + _i * 8192), 16, 0, 0); } while (0)
; #define PG8_LDA(dst, b, h) do { _Pragma("unroll") for (int m = 0; m < 4; ++m) _Pragma("unroll") for (int k = 0; k < 2; ++k) dst[m][k] = *(const PG8_LAS bf16x8*)(lds + PG8_SA(b, h) + aoff + m * 2048 + k * 1024); } while (0)
; #define PG8_LDB(dst, b, h) do { _Pragma("unroll") for (int n = 0; n < 2; ++n) _Pragma("unroll") for (int k = 0; k < 2; ++k) dst[n][k] = *(const PG8_LAS bf16x8*)(lds + PG8_SB(b, h) + boff + n * 2048 + k * 1024); } while (0)
; #define PG8_WAIT_V(n) asm volatile("s_waitcnt vmcnt(" #n ")" ::: "memory")
; #define PG8_WAIT_L(n) asm volatile("s_waitcnt lgkmcnt(" #n ")" ::: "memory")
; #define PG8_BAR __builtin_amdgcn_s_barrier()
; #define PG8_SCHED __builtin_amdgcn_sched_barrier(0)
; template <class Epi, class Sched, bool ALIGN_EPI = false, bool SP2 = false, bool I8 = false>
; __device__ __forceinline__ void gemm_phase(PG8_LAS unsigned char* lds, const Gemm g, const Sched& S, const Epi& E) {
;     ...
;             PG8_LDB(B0, 0, 0); PG8_LDB(B1, 0, 1); PG8_SCHED; PG8_LDA(At, 0, 0); PG8_STAGE(PG8_SA(1, 1), a1 + hstep, voffA);
;             PG8_WAIT_V(8); PG8_WAIT_L(0); PG8_BAR; PG8_MMA(0, 0, At, B0); PG8_MMA(0, 1, At, B1); PG8_BAR; PG8_SCHED;
;             PG8_LDA(At, 0, 1); PG8_STAGE(PG8_SB(0, 0), b2, voffB); PG8_STAGE(PG8_SB(0, 1), b2 + hstep, voffB); PG8_STAGE(PG8_SA(0, 0), a2, voffA);
;             PG8_WAIT_V(8); PG8_WAIT_L(0); PG8_BAR; PG8_MMA(1, 0, At, B0); PG8_MMA(1, 1, At, B1); PG8_BAR; PG8_SCHED;
;             PG8_LDB(B0, 1, 0); PG8_LDB(B1, 1, 1); PG8_SCHED; PG8_LDA(At, 1, 0); PG8_STAGE(PG8_SA(0, 1), a2 + hstep, voffA);
;             PG8_WAIT_V(8); PG8_WAIT_L(0); PG8_BAR; PG8_MMA(0, 0, At, B0); PG8_MMA(0, 1, At, B1); PG8_BAR; PG8_SCHED;
;             PG8_LDA(At, 1, 1); PG8_STAGE(PG8_SB(1, 0), b3, voffB); PG8_STAGE(PG8_SB(1, 1), b3 + hstep, voffB); PG8_STAGE(PG8_SA(1, 0), a3, voffA);
;             PG8_WAIT_V(8); PG8_WAIT_L(0); PG8_BAR; PG8_MMA(1, 0, At, B0); PG8_MMA(1, 1, At, B1); PG8_BAR; PG8_SCHED;
	s_setprio 1
	s_waitcnt lgkmcnt(0)
	v_mfma_i32_16x16x64_i8 v[72:75], v[36:39], v[184:187], v[72:75]
	v_mfma_i32_16x16x64_i8 v[64:67], v[140:143], v[184:187], v[64:67]
	v_mfma_i32_16x16x64_i8 v[56:59], v[36:39], v[204:207], v[56:59]
	v_mfma_i32_16x16x64_i8 v[48:51], v[140:143], v[204:207], v[48:51]
	v_mfma_i32_16x16x64_i8 v[32:35], v[36:39], v[212:215], v[32:35]
	v_mfma_i32_16x16x64_i8 v[24:27], v[140:143], v[212:215], v[24:27]
	v_mfma_i32_16x16x64_i8 v[16:19], v[36:39], v[220:223], v[16:19]
	v_mfma_i32_16x16x64_i8 v[8:11], v[140:143], v[220:223], v[8:11]
	v_mfma_i32_16x16x64_i8 v[72:75], v[44:47], v[188:191], v[72:75]
	v_mfma_i32_16x16x64_i8 v[64:67], v[144:147], v[188:191], v[64:67]
	v_mfma_i32_16x16x64_i8 v[56:59], v[44:47], v[208:211], v[56:59]
	v_mfma_i32_16x16x64_i8 v[48:51], v[144:147], v[208:211], v[48:51]
	v_mfma_i32_16x16x64_i8 v[32:35], v[44:47], v[216:219], v[32:35]
	v_mfma_i32_16x16x64_i8 v[24:27], v[144:147], v[216:219], v[24:27]
	v_mfma_i32_16x16x64_i8 v[16:19], v[44:47], v[224:227], v[16:19]
	v_mfma_i32_16x16x64_i8 v[8:11], v[144:147], v[224:227], v[8:11]
	s_setprio 0
	s_setprio 1
	v_mfma_i32_16x16x64_i8 v[52:55], v[160:163], v[204:207], v[52:55]
	v_mfma_i32_16x16x64_i8 v[40:43], v[176:179], v[204:207], v[40:43]
	v_mfma_i32_16x16x64_i8 v[28:31], v[160:163], v[212:215], v[28:31]
	v_mfma_i32_16x16x64_i8 v[20:23], v[176:179], v[212:215], v[20:23]
	v_mfma_i32_16x16x64_i8 v[12:15], v[160:163], v[220:223], v[12:15]
	v_mfma_i32_16x16x64_i8 v[4:7], v[176:179], v[220:223], v[4:7]
	v_mfma_i32_16x16x64_i8 v[36:39], v[160:163], v[184:187], v[68:71]
	v_mfma_i32_16x16x64_i8 v[44:47], v[176:179], v[184:187], v[60:63]
	v_mfma_i32_16x16x64_i8 v[52:55], v[172:175], v[208:211], v[52:55]
	v_mfma_i32_16x16x64_i8 v[40:43], v[180:183], v[208:211], v[40:43]
	v_mfma_i32_16x16x64_i8 v[28:31], v[172:175], v[216:219], v[28:31]
	v_mfma_i32_16x16x64_i8 v[20:23], v[180:183], v[216:219], v[20:23]
	v_mfma_i32_16x16x64_i8 v[12:15], v[172:175], v[224:227], v[12:15]
	v_mfma_i32_16x16x64_i8 v[4:7], v[180:183], v[224:227], v[4:7]
	v_mfma_i32_16x16x64_i8 v[36:39], v[172:175], v[188:191], v[36:39]
	v_mfma_i32_16x16x64_i8 v[44:47], v[180:183], v[188:191], v[44:47]
	s_setprio 0
	s_barrier
	s_add_i32 s64, 0, 0x18000
	s_add_i32 s65, 0, 0x1c000
	v_add_u32_e32 v144, s64, v167
	v_add_u32_e32 v158, s65, v167
	ds_read_b128 v[60:63], v144
	ds_read_b128 v[68:71], v144 offset:1024
	ds_read_b128 v[140:143], v144 offset:2048
	ds_read_b128 v[144:147], v144 offset:3072
	ds_read_b128 v[160:163], v158
	ds_read_b128 v[172:175], v158 offset:1024
	ds_read_b128 v[176:179], v158 offset:2048
	ds_read_b128 v[180:183], v158 offset:3072
	s_add_u32 s48, s48, 0x80000
	s_addc_u32 s49, s49, 0
	s_mov_b32 m0, s52
	v_lshl_add_u64 v[244:245], s[48:49], 0, v[152:153]
	ds_read_b128 v[184:187], v171 offset:32768
	ds_read_b128 v[188:191], v171 offset:33792
	ds_read_b128 v[204:207], v171 offset:34816
	ds_read_b128 v[208:211], v171 offset:35840
	ds_read_b128 v[212:215], v171 offset:36864
	ds_read_b128 v[216:219], v171 offset:37888
	ds_read_b128 v[220:223], v171 offset:38912
	ds_read_b128 v[224:227], v171 offset:39936
	global_load_lds_dwordx4 v[244:245], off
	v_lshl_add_u64 v[244:245], s[48:49], 0, v[150:151]
	s_mov_b32 m0, s53
	s_nop 0
	global_load_lds_dwordx4 v[244:245], off
	s_waitcnt vmcnt(8)
	s_waitcnt lgkmcnt(0)
	s_barrier
	s_setprio 1
	s_waitcnt lgkmcnt(0)
	v_mfma_i32_16x16x64_i8 v[136:139], v[60:63], v[184:187], v[136:139]
	v_mfma_i32_16x16x64_i8 v[128:131], v[140:143], v[184:187], v[128:131]
	v_mfma_i32_16x16x64_i8 v[120:123], v[60:63], v[204:207], v[120:123]
	v_mfma_i32_16x16x64_i8 v[112:115], v[140:143], v[204:207], v[112:115]
	v_mfma_i32_16x16x64_i8 v[104:107], v[60:63], v[212:215], v[104:107]
	v_mfma_i32_16x16x64_i8 v[96:99], v[140:143], v[212:215], v[96:99]
	v_mfma_i32_16x16x64_i8 v[88:91], v[60:63], v[220:223], v[88:91]
	v_mfma_i32_16x16x64_i8 v[80:83], v[140:143], v[220:223], v[80:83]
	v_mfma_i32_16x16x64_i8 v[136:139], v[68:71], v[188:191], v[136:139]
	v_mfma_i32_16x16x64_i8 v[128:131], v[144:147], v[188:191], v[128:131]
	v_mfma_i32_16x16x64_i8 v[120:123], v[68:71], v[208:211], v[120:123]
	v_mfma_i32_16x16x64_i8 v[112:115], v[144:147], v[208:211], v[112:115]
	v_mfma_i32_16x16x64_i8 v[104:107], v[68:71], v[216:219], v[104:107]
	v_mfma_i32_16x16x64_i8 v[96:99], v[144:147], v[216:219], v[96:99]
	v_mfma_i32_16x16x64_i8 v[88:91], v[68:71], v[224:227], v[88:91]
	v_mfma_i32_16x16x64_i8 v[80:83], v[144:147], v[224:227], v[80:83]
	s_setprio 0
	s_setprio 1
	v_mfma_i32_16x16x64_i8 v[132:135], v[160:163], v[184:187], v[132:135]
	v_mfma_i32_16x16x64_i8 v[124:127], v[176:179], v[184:187], v[124:127]
	v_mfma_i32_16x16x64_i8 v[116:119], v[160:163], v[204:207], v[116:119]
	v_mfma_i32_16x16x64_i8 v[108:111], v[176:179], v[204:207], v[108:111]
	v_mfma_i32_16x16x64_i8 v[100:103], v[160:163], v[212:215], v[100:103]
	v_mfma_i32_16x16x64_i8 v[92:95], v[176:179], v[212:215], v[92:95]
	v_mfma_i32_16x16x64_i8 v[84:87], v[160:163], v[220:223], v[84:87]
	v_mfma_i32_16x16x64_i8 v[76:79], v[176:179], v[220:223], v[76:79]
	v_mfma_i32_16x16x64_i8 v[132:135], v[172:175], v[188:191], v[132:135]
	v_mfma_i32_16x16x64_i8 v[124:127], v[180:183], v[188:191], v[124:127]
	v_mfma_i32_16x16x64_i8 v[116:119], v[172:175], v[208:211], v[116:119]
	v_mfma_i32_16x16x64_i8 v[108:111], v[180:183], v[208:211], v[108:111]
	v_mfma_i32_16x16x64_i8 v[100:103], v[172:175], v[216:219], v[100:103]
	v_mfma_i32_16x16x64_i8 v[92:95], v[180:183], v[216:219], v[92:95]
	v_mfma_i32_16x16x64_i8 v[84:87], v[172:175], v[224:227], v[84:87]
	v_mfma_i32_16x16x64_i8 v[76:79], v[180:183], v[224:227], v[76:79]
	s_setprio 0
	s_barrier
; #define PG8_STAGE(bufoff, gbase, voff) do { _Pragma("unroll") for (int _i = 0; _i < 2; ++_i) \
;         __builtin_amdgcn_global_load_lds((const unsigned*)((const char*)(gbase) + (voff)[_i]), (PG8_LAS unsigned*)(lds + (bufoff) + ldsw + _i * 8192), 16, 0, 0); } while (0)
; #define PG8_LDA(dst, b, h) do { _Pragma("unroll") for (int m = 0; m < 4; ++m) _Pragma("unroll") for (int k = 0; k < 2; ++k) dst[m][k] = *(const PG8_LAS bf16x8*)(lds + PG8_SA(b, h) + aoff + m * 2048 + k * 1024); } while (0)
; #define PG8_LDB(dst, b, h) do { _Pragma("unroll") for (int n = 0; n < 2; ++n) _Pragma("unroll") for (int k = 0; k < 2; ++k) dst[n][k] = *(const PG8_LAS bf16x8*)(lds + PG8_SB(b, h) + boff + n * 2048 + k * 1024); } while (0)
; #define PG8_WAIT_V(n) asm volatile("s_waitcnt vmcnt(" #n ")" ::: "memory")
; #define PG8_WAIT_L(n) asm volatile("s_waitcnt lgkmcnt(" #n ")" ::: "memory")
; #define PG8_BAR __builtin_amdgcn_s_barrier()
; #define PG8_SCHED __builtin_amdgcn_sched_barrier(0)
; template <class Epi, class Sched, bool ALIGN_EPI = false, bool SP2 = false, bool I8 = false>
; __device__ __forceinline__ void gemm_phase(PG8_LAS unsigned char* lds, const Gemm g, const Sched& S, const Epi& E) {
;     ...
;             PG8_LDB(B0, 0, 0); PG8_LDB(B1, 0, 1); PG8_SCHED; PG8_LDA(At, 0, 0); PG8_STAGE(PG8_SA(1, 1), a1 + hstep, voffA);
;             PG8_WAIT_V(8); PG8_WAIT_L(0); PG8_BAR; PG8_MMA(0, 0, At, B0); PG8_MMA(0, 1, At, B1); PG8_BAR; PG8_SCHED;
;             PG8_LDA(At, 0, 1); PG8_STAGE(PG8_SB(0, 0), b2, voffB); PG8_STAGE(PG8_SB(0, 1), b2 + hstep, voffB); PG8_STAGE(PG8_SA(0, 0), a2, voffA);
;             PG8_WAIT_V(8); PG8_WAIT_L(0); PG8_BAR; PG8_MMA(1, 0, At, B0); PG8_MMA(1, 1, At, B1); PG8_BAR; PG8_SCHED;
;             PG8_LDB(B0, 1, 0); PG8_LDB(B1, 1, 1); PG8_SCHED; PG8_LDA(At, 1, 0); PG8_STAGE(PG8_SA(0, 1), a2 + hstep, voffA);
;             PG8_WAIT_V(8); PG8_WAIT_L(0); PG8_BAR; PG8_MMA(0, 0, At, B0); PG8_MMA(0, 1, At, B1); PG8_BAR; PG8_SCHED;
;             PG8_LDA(At, 1, 1); PG8_STAGE(PG8_SB(1, 0), b3, voffB); PG8_STAGE(PG8_SB(1, 1), b3 + hstep, voffB); PG8_STAGE(PG8_SA(1, 0), a3, voffA);
;             PG8_WAIT_V(8); PG8_WAIT_L(0); PG8_BAR; PG8_MMA(1, 0, At, B0); PG8_MMA(1, 1, At, B1); PG8_BAR; PG8_SCHED;
	s_add_i32 s48, s64, s47
	v_lshl_add_u64 v[164:165], v[164:165], 0, s[84:85]
	s_mov_b32 m0, s48
	ds_read_b128 v[184:187], v171 offset:49152
	ds_read_b128 v[188:191], v171 offset:50176
	ds_read_b128 v[204:207], v171 offset:51200
	ds_read_b128 v[208:211], v171 offset:52224
	ds_read_b128 v[212:215], v171 offset:53248
	ds_read_b128 v[216:219], v171 offset:54272
	ds_read_b128 v[220:223], v171 offset:55296
	ds_read_b128 v[224:227], v171 offset:56320
	global_load_lds_dwordx4 v[164:165], off
	s_add_i32 m0, s48, 0x2000
	s_add_u32 s44, s44, 0x80080
	v_lshl_add_u64 v[164:165], v[228:229], 0, s[84:85]
	s_addc_u32 s45, s45, 0
	s_add_i32 s48, s65, s47
	global_load_lds_dwordx4 v[164:165], off
	v_lshl_add_u64 v[164:165], s[44:45], 0, v[2:3]
	s_mov_b32 m0, s48
	s_nop 0
	global_load_lds_dwordx4 v[164:165], off
	v_lshl_add_u64 v[164:165], s[44:45], 0, v[148:149]
	s_add_i32 m0, s48, 0x2000
	s_nop 0
	global_load_lds_dwordx4 v[164:165], off
	v_lshl_add_u64 v[164:165], v[240:241], 0, s[84:85]
	s_mov_b32 m0, s54
	s_nop 0
	global_load_lds_dwordx4 v[164:165], off
	v_lshl_add_u64 v[164:165], v[242:243], 0, s[84:85]
	s_mov_b32 m0, s55
	s_nop 0
	global_load_lds_dwordx4 v[164:165], off
	s_waitcnt vmcnt(8)
	s_waitcnt lgkmcnt(0)
	s_barrier
	s_setprio 1
	s_waitcnt lgkmcnt(0)
	v_mfma_i32_16x16x64_i8 v[72:75], v[60:63], v[184:187], v[72:75]
	v_mfma_i32_16x16x64_i8 v[64:67], v[140:143], v[184:187], v[64:67]
	v_mfma_i32_16x16x64_i8 v[56:59], v[60:63], v[204:207], v[56:59]
	v_mfma_i32_16x16x64_i8 v[48:51], v[140:143], v[204:207], v[48:51]
	v_mfma_i32_16x16x64_i8 v[32:35], v[60:63], v[212:215], v[32:35]
	v_mfma_i32_16x16x64_i8 v[24:27], v[140:143], v[212:215], v[24:27]
	v_mfma_i32_16x16x64_i8 v[16:19], v[60:63], v[220:223], v[16:19]
	v_mfma_i32_16x16x64_i8 v[8:11], v[140:143], v[220:223], v[8:11]
	v_mfma_i32_16x16x64_i8 v[72:75], v[68:71], v[188:191], v[72:75]
	v_mfma_i32_16x16x64_i8 v[64:67], v[144:147], v[188:191], v[64:67]
	v_mfma_i32_16x16x64_i8 v[56:59], v[68:71], v[208:211], v[56:59]
	v_mfma_i32_16x16x64_i8 v[48:51], v[144:147], v[208:211], v[48:51]
	v_mfma_i32_16x16x64_i8 v[32:35], v[68:71], v[216:219], v[32:35]
	v_mfma_i32_16x16x64_i8 v[24:27], v[144:147], v[216:219], v[24:27]
	v_mfma_i32_16x16x64_i8 v[16:19], v[68:71], v[224:227], v[16:19]
	v_mfma_i32_16x16x64_i8 v[8:11], v[144:147], v[224:227], v[8:11]
	s_setprio 0
	s_setprio 1
	v_mfma_i32_16x16x64_i8 v[36:39], v[160:163], v[184:187], v[36:39]
	v_mfma_i32_16x16x64_i8 v[68:71], v[172:175], v[188:191], v[36:39]
	v_mfma_i32_16x16x64_i8 v[36:39], v[176:179], v[184:187], v[44:47]
	v_mfma_i32_16x16x64_i8 v[60:63], v[180:183], v[188:191], v[36:39]
	v_mfma_i32_16x16x64_i8 v[36:39], v[160:163], v[204:207], v[52:55]
	v_mfma_i32_16x16x64_i8 v[52:55], v[172:175], v[208:211], v[36:39]
	v_mfma_i32_16x16x64_i8 v[36:39], v[176:179], v[204:207], v[40:43]
	v_mfma_i32_16x16x64_i8 v[28:31], v[160:163], v[212:215], v[28:31]
	v_mfma_i32_16x16x64_i8 v[20:23], v[176:179], v[212:215], v[20:23]
	v_mfma_i32_16x16x64_i8 v[12:15], v[160:163], v[220:223], v[12:15]
	v_mfma_i32_16x16x64_i8 v[4:7], v[176:179], v[220:223], v[4:7]
	v_mfma_i32_16x16x64_i8 v[40:43], v[180:183], v[208:211], v[36:39]
	v_mfma_i32_16x16x64_i8 v[28:31], v[172:175], v[216:219], v[28:31]
	v_mfma_i32_16x16x64_i8 v[20:23], v[180:183], v[216:219], v[20:23]
	v_mfma_i32_16x16x64_i8 v[12:15], v[172:175], v[224:227], v[12:15]
	v_mfma_i32_16x16x64_i8 v[4:7], v[180:183], v[224:227], v[4:7]
	s_setprio 0
	s_barrier
	s_add_i32 s61, s61, 2
	s_add_u32 s40, s40, 0x100
	s_addc_u32 s41, s41, 0
	s_add_u32 s59, s59, 0x100
	s_addc_u32 s60, s60, 0
	s_cmp_gt_u32 s61, 29
	s_cbranch_scc0 .LBB0_1591

;     __device__ __forceinline__ void operator()(const i32x4 (&acc)[2][2][4][2], const Unit& u, int wr, int wc, int fr, int fq) const {
;         const int row0 = u.pm * BM + wr * 64 + fr, col0 = u.pn * HALF + wc * 32 + 8 * fq, brow = u.pn * BM + wc * 32 + 8 * fq;
;         const f32x4 dg0 = *(const f32x4*)(DB + brow), dg1 = *(const f32x4*)(DB + brow + 4), du0 = *(const f32x4*)(DB + brow + HALF), du1 = *(const f32x4*)(DB + brow + HALF + 4);
;         float rav[2][4];
; #pragma unroll
;         for (int ai = 0; ai < 2; ++ai)
; #pragma unroll
;             for (int m = 0; m < 4; ++m) rav[ai][m] = RA[row0 + ai * HALF + m * 16];
.LBB0_1594:
	v_lshl_add_u32 v160, s35, 8, v159
	v_lshlrev_b32_e32 v162, 2, v169
	v_lshlrev_b32_e32 v163, 2, v159
	v_add_u32_e32 v162, 0x23800, v162
	v_add_u32_e32 v163, 0x23c00, v163
	ds_read_b128 v[44:47], v162
	ds_read_b128 v[36:39], v162 offset:16
	ds_read_b128 v[144:147], v162 offset:512
	ds_read_b128 v[140:143], v162 offset:528
	ds_read2_b32 v[188:189], v163 offset1:16
	ds_read2_b32 v[180:181], v163 offset0:32 offset1:48
	ds_read2_b32 v[176:177], v163 offset0:128 offset1:144
	ds_read2_b32 v[172:173], v163 offset0:160 offset1:176
	v_lshl_or_b32 v186, s34, 7, v169
	s_movk_i32 s23, 0x5600
	v_lshlrev_b32_e32 v186, 1, v186
	v_mad_u32_u24 v186, v160, s23, v186
	v_mov_b32_e32 v178, 0xbfb8aa3b
	v_mov_b32_e32 v179, 1.0
	v_cvt_f32_i32_e32 v136, v136
	v_cvt_f32_i32_e32 v137, v137
	v_cvt_f32_i32_e32 v138, v138
	v_cvt_f32_i32_e32 v139, v139
	v_cvt_f32_i32_e32 v132, v132
	v_cvt_f32_i32_e32 v133, v133
	v_cvt_f32_i32_e32 v134, v134
	v_cvt_f32_i32_e32 v135, v135
	v_cvt_f32_i32_e32 v128, v128
	v_cvt_f32_i32_e32 v129, v129
	v_cvt_f32_i32_e32 v130, v130
	v_cvt_f32_i32_e32 v131, v131
	v_cvt_f32_i32_e32 v124, v124
	v_cvt_f32_i32_e32 v125, v125
	v_cvt_f32_i32_e32 v126, v126
	v_cvt_f32_i32_e32 v127, v127
	v_cvt_f32_i32_e32 v120, v120
	v_cvt_f32_i32_e32 v121, v121
	v_cvt_f32_i32_e32 v122, v122
	v_cvt_f32_i32_e32 v123, v123
	v_cvt_f32_i32_e32 v116, v116
	v_cvt_f32_i32_e32 v117, v117
	v_cvt_f32_i32_e32 v118, v118
	v_cvt_f32_i32_e32 v119, v119
	v_cvt_f32_i32_e32 v112, v112
	v_cvt_f32_i32_e32 v113, v113
	v_cvt_f32_i32_e32 v114, v114
	v_cvt_f32_i32_e32 v115, v115
	v_cvt_f32_i32_e32 v108, v108
	v_cvt_f32_i32_e32 v109, v109
	v_cvt_f32_i32_e32 v110, v110
	v_cvt_f32_i32_e32 v111, v111
	v_cvt_f32_i32_e32 v104, v104
	v_cvt_f32_i32_e32 v105, v105
	v_cvt_f32_i32_e32 v106, v106
	v_cvt_f32_i32_e32 v107, v107
	v_cvt_f32_i32_e32 v100, v100
	v_cvt_f32_i32_e32 v101, v101
	v_cvt_f32_i32_e32 v102, v102
	v_cvt_f32_i32_e32 v103, v103
	v_cvt_f32_i32_e32 v96, v96
	v_cvt_f32_i32_e32 v97, v97
	v_cvt_f32_i32_e32 v98, v98
	v_cvt_f32_i32_e32 v99, v99
	v_cvt_f32_i32_e32 v92, v92
	v_cvt_f32_i32_e32 v93, v93
	v_cvt_f32_i32_e32 v94, v94
	v_cvt_f32_i32_e32 v95, v95
	v_cvt_f32_i32_e32 v88, v88
	v_cvt_f32_i32_e32 v89, v89
	v_cvt_f32_i32_e32 v90, v90
	v_cvt_f32_i32_e32 v91, v91
	v_cvt_f32_i32_e32 v84, v84
	v_cvt_f32_i32_e32 v85, v85
	v_cvt_f32_i32_e32 v86, v86
	v_cvt_f32_i32_e32 v87, v87
	v_cvt_f32_i32_e32 v80, v80
	v_cvt_f32_i32_e32 v81, v81
	v_cvt_f32_i32_e32 v82, v82
	v_cvt_f32_i32_e32 v83, v83
	v_cvt_f32_i32_e32 v76, v76
	v_cvt_f32_i32_e32 v77, v77
	v_cvt_f32_i32_e32 v78, v78
	v_cvt_f32_i32_e32 v79, v79
	v_cvt_f32_i32_e32 v72, v72
	v_cvt_f32_i32_e32 v73, v73
	v_cvt_f32_i32_e32 v74, v74
	v_cvt_f32_i32_e32 v75, v75
	v_cvt_f32_i32_e32 v68, v68
	v_cvt_f32_i32_e32 v69, v69
	v_cvt_f32_i32_e32 v70, v70
	v_cvt_f32_i32_e32 v71, v71
	v_cvt_f32_i32_e32 v64, v64
	v_cvt_f32_i32_e32 v65, v65
	v_cvt_f32_i32_e32 v66, v66
	v_cvt_f32_i32_e32 v67, v67
	v_cvt_f32_i32_e32 v60, v60
	v_cvt_f32_i32_e32 v61, v61
	v_cvt_f32_i32_e32 v62, v62
	v_cvt_f32_i32_e32 v63, v63
	v_cvt_f32_i32_e32 v56, v56
	v_cvt_f32_i32_e32 v57, v57
	v_cvt_f32_i32_e32 v58, v58
	v_cvt_f32_i32_e32 v59, v59
	v_cvt_f32_i32_e32 v52, v52
	v_cvt_f32_i32_e32 v53, v53
	v_cvt_f32_i32_e32 v54, v54
	v_cvt_f32_i32_e32 v55, v55
	v_cvt_f32_i32_e32 v48, v48
	v_cvt_f32_i32_e32 v49, v49
	v_cvt_f32_i32_e32 v50, v50
	v_cvt_f32_i32_e32 v51, v51
	v_cvt_f32_i32_e32 v40, v40
	v_cvt_f32_i32_e32 v41, v41
	v_cvt_f32_i32_e32 v42, v42
	v_cvt_f32_i32_e32 v43, v43
	v_cvt_f32_i32_e32 v32, v32
	v_cvt_f32_i32_e32 v33, v33
	v_cvt_f32_i32_e32 v34, v34
	v_cvt_f32_i32_e32 v35, v35
	v_cvt_f32_i32_e32 v28, v28
	v_cvt_f32_i32_e32 v29, v29
	v_cvt_f32_i32_e32 v30, v30
	v_cvt_f32_i32_e32 v31, v31
	v_cvt_f32_i32_e32 v24, v24
	v_cvt_f32_i32_e32 v25, v25
	v_cvt_f32_i32_e32 v26, v26
	v_cvt_f32_i32_e32 v27, v27
	v_cvt_f32_i32_e32 v20, v20
	v_cvt_f32_i32_e32 v21, v21
	v_cvt_f32_i32_e32 v22, v22
	v_cvt_f32_i32_e32 v23, v23
	v_cvt_f32_i32_e32 v16, v16
	v_cvt_f32_i32_e32 v17, v17
	v_cvt_f32_i32_e32 v18, v18
	v_cvt_f32_i32_e32 v19, v19
	v_cvt_f32_i32_e32 v12, v12
	v_cvt_f32_i32_e32 v13, v13
	v_cvt_f32_i32_e32 v14, v14
	v_cvt_f32_i32_e32 v15, v15
	v_cvt_f32_i32_e32 v8, v8
	v_cvt_f32_i32_e32 v9, v9
	v_cvt_f32_i32_e32 v10, v10
	v_cvt_f32_i32_e32 v11, v11
	v_cvt_f32_i32_e32 v4, v4
	v_cvt_f32_i32_e32 v5, v5
	v_cvt_f32_i32_e32 v6, v6
	v_cvt_f32_i32_e32 v7, v7
	s_waitcnt lgkmcnt(0)
; __device__ __forceinline__ unsigned cvt_pk_bf16(float lo, float hi) { unsigned r; asm volatile("v_cvt_pk_bf16_f32 %0, %1, %2" : "=v"(r) : "v"(lo), "v"(hi)); return r; }
; __device__ __forceinline__ float fast_sigmoid(float x) { return __builtin_amdgcn_rcpf(1.0f + __expf(-x)); }
;     __device__ __forceinline__ void operator()(const i32x4 (&acc)[2][2][4][2], const Unit& u, int wr, int wc, int fr, int fq) const {
;     ...
; #pragma unroll
;         for (int ai = 0; ai < 2; ++ai)
; #pragma unroll
;             for (int m = 0; m < 4; ++m) { const int row = row0 + ai * HALF + m * 16; const float ra = rav[ai][m]; bf16_t* rowp = H + (size_t)row * ldh + col0;
;                 float hv[8];
; #pragma unroll
;                 for (int j = 0; j < 4; ++j) { const float g0 = (float)acc[ai][0][m][0][j] * ra * dg0[j], u0 = (float)acc[ai][1][m][0][j] * ra * du0[j]; hv[j] = g0 * fast_sigmoid(g0) * u0;
;                     const float g1 = (float)acc[ai][0][m][1][j] * ra * dg1[j], u1 = (float)acc[ai][1][m][1][j] * ra * du1[j]; hv[4 + j] = g1 * fast_sigmoid(g1) * u1; }
;                 u32x4 w; w.x = cvt_pk_bf16(hv[0], hv[1]); w.y = cvt_pk_bf16(hv[2], hv[3]); w.z = cvt_pk_bf16(hv[4], hv[5]); w.w = cvt_pk_bf16(hv[6], hv[7]);
;                 *(u32x4*)rowp = w; }
	v_pk_mul_f32 v[136:137], v[188:189], v[136:137] op_sel_hi:[0,1]
	v_pk_mul_f32 v[132:133], v[188:189], v[132:133] op_sel_hi:[0,1]
	v_pk_mul_f32 v[138:139], v[188:189], v[138:139] op_sel_hi:[0,1]
	v_pk_mul_f32 v[134:135], v[188:189], v[134:135] op_sel_hi:[0,1]
	v_pk_mul_f32 v[128:129], v[188:189], v[128:129] op_sel_hi:[0,1]
	v_pk_mul_f32 v[124:125], v[188:189], v[124:125] op_sel_hi:[0,1]
	v_pk_mul_f32 v[130:131], v[188:189], v[130:131] op_sel_hi:[0,1]
	v_pk_mul_f32 v[126:127], v[188:189], v[126:127] op_sel_hi:[0,1]
	v_pk_mul_f32 v[136:137], v[44:45], v[136:137]
	v_pk_mul_f32 v[132:133], v[144:145], v[132:133]
	v_pk_mul_f32 v[138:139], v[46:47], v[138:139]
	v_pk_mul_f32 v[134:135], v[146:147], v[134:135]
	v_pk_mul_f32 v[128:129], v[36:37], v[128:129]
	v_pk_mul_f32 v[124:125], v[140:141], v[124:125]
	v_pk_mul_f32 v[130:131], v[38:39], v[130:131]
	v_pk_mul_f32 v[126:127], v[142:143], v[126:127]
	v_pk_mul_f32 v[160:161], v[178:179], v[136:137] op_sel_hi:[0,1]
	v_pk_mul_f32 v[162:163], v[178:179], v[138:139] op_sel_hi:[0,1]
	v_exp_f32_e32 v160, v160
	v_exp_f32_e32 v161, v161
	v_exp_f32_e32 v162, v162
	v_exp_f32_e32 v163, v163
	v_pk_add_f32 v[160:161], v[178:179], v[160:161] op_sel:[1,0] op_sel_hi:[1,1]
	v_pk_add_f32 v[162:163], v[178:179], v[162:163] op_sel:[1,0] op_sel_hi:[1,1]
	v_rcp_f32_e32 v160, v160
	v_rcp_f32_e32 v161, v161
	v_rcp_f32_e32 v162, v162
	v_rcp_f32_e32 v163, v163
	v_pk_mul_f32 v[136:137], v[136:137], v[160:161]
	v_pk_mul_f32 v[138:139], v[138:139], v[162:163]
	v_pk_mul_f32 v[136:137], v[132:133], v[136:137]
	v_pk_mul_f32 v[138:139], v[134:135], v[138:139]
	v_pk_mul_f32 v[160:161], v[178:179], v[128:129] op_sel_hi:[0,1]
	v_pk_mul_f32 v[162:163], v[178:179], v[130:131] op_sel_hi:[0,1]
	v_exp_f32_e32 v160, v160
	v_exp_f32_e32 v161, v161
	v_exp_f32_e32 v162, v162
	v_exp_f32_e32 v163, v163
	v_pk_add_f32 v[160:161], v[178:179], v[160:161] op_sel:[1,0] op_sel_hi:[1,1]
	v_pk_add_f32 v[162:163], v[178:179], v[162:163] op_sel:[1,0] op_sel_hi:[1,1]
	v_rcp_f32_e32 v160, v160
	v_rcp_f32_e32 v161, v161
	v_rcp_f32_e32 v162, v162
	v_rcp_f32_e32 v163, v163
	v_pk_mul_f32 v[128:129], v[128:129], v[160:161]
	v_pk_mul_f32 v[130:131], v[130:131], v[162:163]
	v_pk_mul_f32 v[128:129], v[124:125], v[128:129]
	v_pk_mul_f32 v[130:131], v[126:127], v[130:131]
	v_cvt_pk_bf16_f32 v136, v136, v137
	v_cvt_pk_bf16_f32 v137, v138, v139
	v_cvt_pk_bf16_f32 v138, v128, v129
	v_cvt_pk_bf16_f32 v139, v130, v131
	global_store_dwordx4 v186, v[136:139], s[14:15]
	v_pk_mul_f32 v[120:121], v[188:189], v[120:121] op_sel:[1,0] op_sel_hi:[1,1]
	v_pk_mul_f32 v[116:117], v[188:189], v[116:117] op_sel:[1,0] op_sel_hi:[1,1]
	v_pk_mul_f32 v[122:123], v[188:189], v[122:123] op_sel:[1,0] op_sel_hi:[1,1]
	v_pk_mul_f32 v[118:119], v[188:189], v[118:119] op_sel:[1,0] op_sel_hi:[1,1]
	v_pk_mul_f32 v[112:113], v[188:189], v[112:113] op_sel:[1,0] op_sel_hi:[1,1]
	v_pk_mul_f32 v[108:109], v[188:189], v[108:109] op_sel:[1,0] op_sel_hi:[1,1]
	v_pk_mul_f32 v[114:115], v[188:189], v[114:115] op_sel:[1,0] op_sel_hi:[1,1]
	v_pk_mul_f32 v[110:111], v[188:189], v[110:111] op_sel:[1,0] op_sel_hi:[1,1]
	v_pk_mul_f32 v[120:121], v[44:45], v[120:121]
	v_pk_mul_f32 v[116:117], v[144:145], v[116:117]
	v_pk_mul_f32 v[122:123], v[46:47], v[122:123]
	v_pk_mul_f32 v[118:119], v[146:147], v[118:119]
	v_pk_mul_f32 v[112:113], v[36:37], v[112:113]
	v_pk_mul_f32 v[108:109], v[140:141], v[108:109]
	v_pk_mul_f32 v[114:115], v[38:39], v[114:115]
	v_pk_mul_f32 v[110:111], v[142:143], v[110:111]
	v_pk_mul_f32 v[160:161], v[178:179], v[120:121] op_sel_hi:[0,1]
	v_pk_mul_f32 v[162:163], v[178:179], v[122:123] op_sel_hi:[0,1]
	v_exp_f32_e32 v160, v160
	v_exp_f32_e32 v161, v161
	v_exp_f32_e32 v162, v162
	v_exp_f32_e32 v163, v163
	v_pk_add_f32 v[160:161], v[178:179], v[160:161] op_sel:[1,0] op_sel_hi:[1,1]
	v_pk_add_f32 v[162:163], v[178:179], v[162:163] op_sel:[1,0] op_sel_hi:[1,1]
	v_rcp_f32_e32 v160, v160
	v_rcp_f32_e32 v161, v161
	v_rcp_f32_e32 v162, v162
	v_rcp_f32_e32 v163, v163
	v_pk_mul_f32 v[120:121], v[120:121], v[160:161]
	v_pk_mul_f32 v[122:123], v[122:123], v[162:163]
	v_pk_mul_f32 v[120:121], v[116:117], v[120:121]
	v_pk_mul_f32 v[122:123], v[118:119], v[122:123]
	v_pk_mul_f32 v[160:161], v[178:179], v[112:113] op_sel_hi:[0,1]
	v_pk_mul_f32 v[162:163], v[178:179], v[114:115] op_sel_hi:[0,1]
	v_exp_f32_e32 v160, v160
	v_exp_f32_e32 v161, v161
	v_exp_f32_e32 v162, v162
	v_exp_f32_e32 v163, v163
	v_pk_add_f32 v[160:161], v[178:179], v[160:161] op_sel:[1,0] op_sel_hi:[1,1]
	v_pk_add_f32 v[162:163], v[178:179], v[162:163] op_sel:[1,0] op_sel_hi:[1,1]
	v_rcp_f32_e32 v160, v160
	v_rcp_f32_e32 v161, v161
	v_rcp_f32_e32 v162, v162
	v_rcp_f32_e32 v163, v163
	v_pk_mul_f32 v[112:113], v[112:113], v[160:161]
	v_pk_mul_f32 v[114:115], v[114:115], v[162:163]
	v_pk_mul_f32 v[112:113], v[108:109], v[112:113]
	v_pk_mul_f32 v[114:115], v[110:111], v[114:115]
	v_cvt_pk_bf16_f32 v120, v120, v121
	v_cvt_pk_bf16_f32 v121, v122, v123
	v_cvt_pk_bf16_f32 v122, v112, v113
	v_cvt_pk_bf16_f32 v123, v114, v115
	v_add_u32_e32 v187, 0x56000, v186
	global_store_dwordx4 v187, v[120:123], s[14:15]
	v_pk_mul_f32 v[104:105], v[180:181], v[104:105] op_sel_hi:[0,1]
	v_pk_mul_f32 v[100:101], v[180:181], v[100:101] op_sel_hi:[0,1]
	v_pk_mul_f32 v[106:107], v[180:181], v[106:107] op_sel_hi:[0,1]
	v_pk_mul_f32 v[102:103], v[180:181], v[102:103] op_sel_hi:[0,1]
	v_pk_mul_f32 v[96:97], v[180:181], v[96:97] op_sel_hi:[0,1]
	v_pk_mul_f32 v[92:93], v[180:181], v[92:93] op_sel_hi:[0,1]
	v_pk_mul_f32 v[98:99], v[180:181], v[98:99] op_sel_hi:[0,1]
	v_pk_mul_f32 v[94:95], v[180:181], v[94:95] op_sel_hi:[0,1]
	v_pk_mul_f32 v[104:105], v[44:45], v[104:105]
; __device__ __forceinline__ unsigned cvt_pk_bf16(float lo, float hi) { unsigned r; asm volatile("v_cvt_pk_bf16_f32 %0, %1, %2" : "=v"(r) : "v"(lo), "v"(hi)); return r; }
; __device__ __forceinline__ float fast_sigmoid(float x) { return __builtin_amdgcn_rcpf(1.0f + __expf(-x)); }
;     __device__ __forceinline__ void operator()(const i32x4 (&acc)[2][2][4][2], const Unit& u, int wr, int wc, int fr, int fq) const {
;     ...
; #pragma unroll
;         for (int ai = 0; ai < 2; ++ai)
; #pragma unroll
;             for (int m = 0; m < 4; ++m) { const int row = row0 + ai * HALF + m * 16; const float ra = rav[ai][m]; bf16_t* rowp = H + (size_t)row * ldh + col0;
;                 float hv[8];
; #pragma unroll
;                 for (int j = 0; j < 4; ++j) { const float g0 = (float)acc[ai][0][m][0][j] * ra * dg0[j], u0 = (float)acc[ai][1][m][0][j] * ra * du0[j]; hv[j] = g0 * fast_sigmoid(g0) * u0;
;                     const float g1 = (float)acc[ai][0][m][1][j] * ra * dg1[j], u1 = (float)acc[ai][1][m][1][j] * ra * du1[j]; hv[4 + j] = g1 * fast_sigmoid(g1) * u1; }
;                 u32x4 w; w.x = cvt_pk_bf16(hv[0], hv[1]); w.y = cvt_pk_bf16(hv[2], hv[3]); w.z = cvt_pk_bf16(hv[4], hv[5]); w.w = cvt_pk_bf16(hv[6], hv[7]);
;                 *(u32x4*)rowp = w; }
	v_pk_mul_f32 v[100:101], v[144:145], v[100:101]
	v_pk_mul_f32 v[106:107], v[46:47], v[106:107]
	v_pk_mul_f32 v[102:103], v[146:147], v[102:103]
	v_pk_mul_f32 v[96:97], v[36:37], v[96:97]
	v_pk_mul_f32 v[92:93], v[140:141], v[92:93]
	v_pk_mul_f32 v[98:99], v[38:39], v[98:99]
	v_pk_mul_f32 v[94:95], v[142:143], v[94:95]
	v_pk_mul_f32 v[160:161], v[178:179], v[104:105] op_sel_hi:[0,1]
	v_pk_mul_f32 v[162:163], v[178:179], v[106:107] op_sel_hi:[0,1]
	v_exp_f32_e32 v160, v160
	v_exp_f32_e32 v161, v161
	v_exp_f32_e32 v162, v162
	v_exp_f32_e32 v163, v163
	v_pk_add_f32 v[160:161], v[178:179], v[160:161] op_sel:[1,0] op_sel_hi:[1,1]
	v_pk_add_f32 v[162:163], v[178:179], v[162:163] op_sel:[1,0] op_sel_hi:[1,1]
	v_rcp_f32_e32 v160, v160
	v_rcp_f32_e32 v161, v161
	v_rcp_f32_e32 v162, v162
	v_rcp_f32_e32 v163, v163
	v_pk_mul_f32 v[104:105], v[104:105], v[160:161]
	v_pk_mul_f32 v[106:107], v[106:107], v[162:163]
	v_pk_mul_f32 v[104:105], v[100:101], v[104:105]
	v_pk_mul_f32 v[106:107], v[102:103], v[106:107]
	v_pk_mul_f32 v[160:161], v[178:179], v[96:97] op_sel_hi:[0,1]
	v_pk_mul_f32 v[162:163], v[178:179], v[98:99] op_sel_hi:[0,1]
	v_exp_f32_e32 v160, v160
	v_exp_f32_e32 v161, v161
	v_exp_f32_e32 v162, v162
	v_exp_f32_e32 v163, v163
	v_pk_add_f32 v[160:161], v[178:179], v[160:161] op_sel:[1,0] op_sel_hi:[1,1]
	v_pk_add_f32 v[162:163], v[178:179], v[162:163] op_sel:[1,0] op_sel_hi:[1,1]
	v_rcp_f32_e32 v160, v160
	v_rcp_f32_e32 v161, v161
	v_rcp_f32_e32 v162, v162
	v_rcp_f32_e32 v163, v163
	v_pk_mul_f32 v[96:97], v[96:97], v[160:161]
	v_pk_mul_f32 v[98:99], v[98:99], v[162:163]
	v_pk_mul_f32 v[96:97], v[92:93], v[96:97]
	v_pk_mul_f32 v[98:99], v[94:95], v[98:99]
	v_cvt_pk_bf16_f32 v104, v104, v105
	v_cvt_pk_bf16_f32 v105, v106, v107
	v_cvt_pk_bf16_f32 v106, v96, v97
	v_cvt_pk_bf16_f32 v107, v98, v99
	v_add_u32_e32 v187, 0xac000, v186
	global_store_dwordx4 v187, v[104:107], s[14:15]
	v_pk_mul_f32 v[88:89], v[180:181], v[88:89] op_sel:[1,0] op_sel_hi:[1,1]
	v_pk_mul_f32 v[84:85], v[180:181], v[84:85] op_sel:[1,0] op_sel_hi:[1,1]
	v_pk_mul_f32 v[90:91], v[180:181], v[90:91] op_sel:[1,0] op_sel_hi:[1,1]
	v_pk_mul_f32 v[86:87], v[180:181], v[86:87] op_sel:[1,0] op_sel_hi:[1,1]
	v_pk_mul_f32 v[80:81], v[180:181], v[80:81] op_sel:[1,0] op_sel_hi:[1,1]
	v_pk_mul_f32 v[76:77], v[180:181], v[76:77] op_sel:[1,0] op_sel_hi:[1,1]
	v_pk_mul_f32 v[82:83], v[180:181], v[82:83] op_sel:[1,0] op_sel_hi:[1,1]
	v_pk_mul_f32 v[78:79], v[180:181], v[78:79] op_sel:[1,0] op_sel_hi:[1,1]
	v_pk_mul_f32 v[88:89], v[44:45], v[88:89]
	v_pk_mul_f32 v[84:85], v[144:145], v[84:85]
	v_pk_mul_f32 v[90:91], v[46:47], v[90:91]
	v_pk_mul_f32 v[86:87], v[146:147], v[86:87]
	v_pk_mul_f32 v[80:81], v[36:37], v[80:81]
	v_pk_mul_f32 v[76:77], v[140:141], v[76:77]
	v_pk_mul_f32 v[82:83], v[38:39], v[82:83]
	v_pk_mul_f32 v[78:79], v[142:143], v[78:79]
	v_pk_mul_f32 v[160:161], v[178:179], v[88:89] op_sel_hi:[0,1]
	v_pk_mul_f32 v[162:163], v[178:179], v[90:91] op_sel_hi:[0,1]
	v_exp_f32_e32 v160, v160
	v_exp_f32_e32 v161, v161
	v_exp_f32_e32 v162, v162
	v_exp_f32_e32 v163, v163
	v_pk_add_f32 v[160:161], v[178:179], v[160:161] op_sel:[1,0] op_sel_hi:[1,1]
	v_pk_add_f32 v[162:163], v[178:179], v[162:163] op_sel:[1,0] op_sel_hi:[1,1]
	v_rcp_f32_e32 v160, v160
	v_rcp_f32_e32 v161, v161
	v_rcp_f32_e32 v162, v162
	v_rcp_f32_e32 v163, v163
	v_pk_mul_f32 v[88:89], v[88:89], v[160:161]
	v_pk_mul_f32 v[90:91], v[90:91], v[162:163]
	v_pk_mul_f32 v[88:89], v[84:85], v[88:89]
	v_pk_mul_f32 v[90:91], v[86:87], v[90:91]
	v_pk_mul_f32 v[160:161], v[178:179], v[80:81] op_sel_hi:[0,1]
	v_pk_mul_f32 v[162:163], v[178:179], v[82:83] op_sel_hi:[0,1]
	v_exp_f32_e32 v160, v160
	v_exp_f32_e32 v161, v161
	v_exp_f32_e32 v162, v162
	v_exp_f32_e32 v163, v163
	v_pk_add_f32 v[160:161], v[178:179], v[160:161] op_sel:[1,0] op_sel_hi:[1,1]
	v_pk_add_f32 v[162:163], v[178:179], v[162:163] op_sel:[1,0] op_sel_hi:[1,1]
	v_rcp_f32_e32 v160, v160
	v_rcp_f32_e32 v161, v161
	v_rcp_f32_e32 v162, v162
	v_rcp_f32_e32 v163, v163
	v_pk_mul_f32 v[80:81], v[80:81], v[160:161]
	v_pk_mul_f32 v[82:83], v[82:83], v[162:163]
	v_pk_mul_f32 v[80:81], v[76:77], v[80:81]
	v_pk_mul_f32 v[82:83], v[78:79], v[82:83]
	v_cvt_pk_bf16_f32 v88, v88, v89
	v_cvt_pk_bf16_f32 v89, v90, v91
	v_cvt_pk_bf16_f32 v90, v80, v81
	v_cvt_pk_bf16_f32 v91, v82, v83
	v_add_u32_e32 v187, 0x102000, v186
	global_store_dwordx4 v187, v[88:91], s[14:15]
	v_pk_mul_f32 v[72:73], v[176:177], v[72:73] op_sel_hi:[0,1]
	v_pk_mul_f32 v[68:69], v[176:177], v[68:69] op_sel_hi:[0,1]
	v_pk_mul_f32 v[74:75], v[176:177], v[74:75] op_sel_hi:[0,1]
	v_pk_mul_f32 v[70:71], v[176:177], v[70:71] op_sel_hi:[0,1]
	v_pk_mul_f32 v[64:65], v[176:177], v[64:65] op_sel_hi:[0,1]
	v_pk_mul_f32 v[60:61], v[176:177], v[60:61] op_sel_hi:[0,1]
	v_pk_mul_f32 v[66:67], v[176:177], v[66:67] op_sel_hi:[0,1]
	v_pk_mul_f32 v[62:63], v[176:177], v[62:63] op_sel_hi:[0,1]
	v_pk_mul_f32 v[72:73], v[44:45], v[72:73]
	v_pk_mul_f32 v[68:69], v[144:145], v[68:69]
	v_pk_mul_f32 v[74:75], v[46:47], v[74:75]
	v_pk_mul_f32 v[70:71], v[146:147], v[70:71]
	v_pk_mul_f32 v[64:65], v[36:37], v[64:65]
	v_pk_mul_f32 v[60:61], v[140:141], v[60:61]
	v_pk_mul_f32 v[66:67], v[38:39], v[66:67]
	v_pk_mul_f32 v[62:63], v[142:143], v[62:63]
	v_pk_mul_f32 v[160:161], v[178:179], v[72:73] op_sel_hi:[0,1]
	v_pk_mul_f32 v[162:163], v[178:179], v[74:75] op_sel_hi:[0,1]
	v_exp_f32_e32 v160, v160
	v_exp_f32_e32 v161, v161
	v_exp_f32_e32 v162, v162
	v_exp_f32_e32 v163, v163
	v_pk_add_f32 v[160:161], v[178:179], v[160:161] op_sel:[1,0] op_sel_hi:[1,1]
	v_pk_add_f32 v[162:163], v[178:179], v[162:163] op_sel:[1,0] op_sel_hi:[1,1]
	v_rcp_f32_e32 v160, v160
; __device__ __forceinline__ unsigned cvt_pk_bf16(float lo, float hi) { unsigned r; asm volatile("v_cvt_pk_bf16_f32 %0, %1, %2" : "=v"(r) : "v"(lo), "v"(hi)); return r; }
; __device__ __forceinline__ float fast_sigmoid(float x) { return __builtin_amdgcn_rcpf(1.0f + __expf(-x)); }
;     __device__ __forceinline__ void operator()(const i32x4 (&acc)[2][2][4][2], const Unit& u, int wr, int wc, int fr, int fq) const {
;     ...
; #pragma unroll
;         for (int ai = 0; ai < 2; ++ai)
; #pragma unroll
;             for (int m = 0; m < 4; ++m) { const int row = row0 + ai * HALF + m * 16; const float ra = rav[ai][m]; bf16_t* rowp = H + (size_t)row * ldh + col0;
;                 float hv[8];
; #pragma unroll
;                 for (int j = 0; j < 4; ++j) { const float g0 = (float)acc[ai][0][m][0][j] * ra * dg0[j], u0 = (float)acc[ai][1][m][0][j] * ra * du0[j]; hv[j] = g0 * fast_sigmoid(g0) * u0;
;                     const float g1 = (float)acc[ai][0][m][1][j] * ra * dg1[j], u1 = (float)acc[ai][1][m][1][j] * ra * du1[j]; hv[4 + j] = g1 * fast_sigmoid(g1) * u1; }
;                 u32x4 w; w.x = cvt_pk_bf16(hv[0], hv[1]); w.y = cvt_pk_bf16(hv[2], hv[3]); w.z = cvt_pk_bf16(hv[4], hv[5]); w.w = cvt_pk_bf16(hv[6], hv[7]);
;                 *(u32x4*)rowp = w; }
	v_rcp_f32_e32 v161, v161
	v_rcp_f32_e32 v162, v162
	v_rcp_f32_e32 v163, v163
	v_pk_mul_f32 v[72:73], v[72:73], v[160:161]
	v_pk_mul_f32 v[74:75], v[74:75], v[162:163]
	v_pk_mul_f32 v[72:73], v[68:69], v[72:73]
	v_pk_mul_f32 v[74:75], v[70:71], v[74:75]
	v_pk_mul_f32 v[160:161], v[178:179], v[64:65] op_sel_hi:[0,1]
	v_pk_mul_f32 v[162:163], v[178:179], v[66:67] op_sel_hi:[0,1]
	v_exp_f32_e32 v160, v160
	v_exp_f32_e32 v161, v161
	v_exp_f32_e32 v162, v162
	v_exp_f32_e32 v163, v163
	v_pk_add_f32 v[160:161], v[178:179], v[160:161] op_sel:[1,0] op_sel_hi:[1,1]
	v_pk_add_f32 v[162:163], v[178:179], v[162:163] op_sel:[1,0] op_sel_hi:[1,1]
	v_rcp_f32_e32 v160, v160
	v_rcp_f32_e32 v161, v161
	v_rcp_f32_e32 v162, v162
	v_rcp_f32_e32 v163, v163
	v_pk_mul_f32 v[64:65], v[64:65], v[160:161]
	v_pk_mul_f32 v[66:67], v[66:67], v[162:163]
	v_pk_mul_f32 v[64:65], v[60:61], v[64:65]
	v_pk_mul_f32 v[66:67], v[62:63], v[66:67]
	v_cvt_pk_bf16_f32 v72, v72, v73
	v_cvt_pk_bf16_f32 v73, v74, v75
	v_cvt_pk_bf16_f32 v74, v64, v65
	v_cvt_pk_bf16_f32 v75, v66, v67
	v_add_u32_e32 v187, 0x2b0000, v186
	global_store_dwordx4 v187, v[72:75], s[14:15]
	v_pk_mul_f32 v[56:57], v[176:177], v[56:57] op_sel:[1,0] op_sel_hi:[1,1]
	v_pk_mul_f32 v[52:53], v[176:177], v[52:53] op_sel:[1,0] op_sel_hi:[1,1]
	v_pk_mul_f32 v[58:59], v[176:177], v[58:59] op_sel:[1,0] op_sel_hi:[1,1]
	v_pk_mul_f32 v[54:55], v[176:177], v[54:55] op_sel:[1,0] op_sel_hi:[1,1]
	v_pk_mul_f32 v[48:49], v[176:177], v[48:49] op_sel:[1,0] op_sel_hi:[1,1]
	v_pk_mul_f32 v[40:41], v[176:177], v[40:41] op_sel:[1,0] op_sel_hi:[1,1]
	v_pk_mul_f32 v[50:51], v[176:177], v[50:51] op_sel:[1,0] op_sel_hi:[1,1]
	v_pk_mul_f32 v[42:43], v[176:177], v[42:43] op_sel:[1,0] op_sel_hi:[1,1]
	v_pk_mul_f32 v[56:57], v[44:45], v[56:57]
	v_pk_mul_f32 v[52:53], v[144:145], v[52:53]
	v_pk_mul_f32 v[58:59], v[46:47], v[58:59]
	v_pk_mul_f32 v[54:55], v[146:147], v[54:55]
	v_pk_mul_f32 v[48:49], v[36:37], v[48:49]
	v_pk_mul_f32 v[40:41], v[140:141], v[40:41]
	v_pk_mul_f32 v[50:51], v[38:39], v[50:51]
	v_pk_mul_f32 v[42:43], v[142:143], v[42:43]
	v_pk_mul_f32 v[160:161], v[178:179], v[56:57] op_sel_hi:[0,1]
	v_pk_mul_f32 v[162:163], v[178:179], v[58:59] op_sel_hi:[0,1]
	v_exp_f32_e32 v160, v160
	v_exp_f32_e32 v161, v161
	v_exp_f32_e32 v162, v162
	v_exp_f32_e32 v163, v163
	v_pk_add_f32 v[160:161], v[178:179], v[160:161] op_sel:[1,0] op_sel_hi:[1,1]
	v_pk_add_f32 v[162:163], v[178:179], v[162:163] op_sel:[1,0] op_sel_hi:[1,1]
	v_rcp_f32_e32 v160, v160
	v_rcp_f32_e32 v161, v161
	v_rcp_f32_e32 v162, v162
	v_rcp_f32_e32 v163, v163
	v_pk_mul_f32 v[56:57], v[56:57], v[160:161]
	v_pk_mul_f32 v[58:59], v[58:59], v[162:163]
	v_pk_mul_f32 v[56:57], v[52:53], v[56:57]
	v_pk_mul_f32 v[58:59], v[54:55], v[58:59]
	v_pk_mul_f32 v[160:161], v[178:179], v[48:49] op_sel_hi:[0,1]
	v_pk_mul_f32 v[162:163], v[178:179], v[50:51] op_sel_hi:[0,1]
	v_exp_f32_e32 v160, v160
	v_exp_f32_e32 v161, v161
	v_exp_f32_e32 v162, v162
	v_exp_f32_e32 v163, v163
	v_pk_add_f32 v[160:161], v[178:179], v[160:161] op_sel:[1,0] op_sel_hi:[1,1]
	v_pk_add_f32 v[162:163], v[178:179], v[162:163] op_sel:[1,0] op_sel_hi:[1,1]
	v_rcp_f32_e32 v160, v160
	v_rcp_f32_e32 v161, v161
	v_rcp_f32_e32 v162, v162
	v_rcp_f32_e32 v163, v163
	v_pk_mul_f32 v[48:49], v[48:49], v[160:161]
	v_pk_mul_f32 v[50:51], v[50:51], v[162:163]
	v_pk_mul_f32 v[48:49], v[40:41], v[48:49]
	v_pk_mul_f32 v[50:51], v[42:43], v[50:51]
	v_cvt_pk_bf16_f32 v56, v56, v57
	v_cvt_pk_bf16_f32 v57, v58, v59
	v_cvt_pk_bf16_f32 v58, v48, v49
	v_cvt_pk_bf16_f32 v59, v50, v51
	v_add_u32_e32 v187, 0x306000, v186
	global_store_dwordx4 v187, v[56:59], s[14:15]
	v_pk_mul_f32 v[32:33], v[172:173], v[32:33] op_sel_hi:[0,1]
	v_pk_mul_f32 v[28:29], v[172:173], v[28:29] op_sel_hi:[0,1]
	v_pk_mul_f32 v[34:35], v[172:173], v[34:35] op_sel_hi:[0,1]
	v_pk_mul_f32 v[30:31], v[172:173], v[30:31] op_sel_hi:[0,1]
	v_pk_mul_f32 v[24:25], v[172:173], v[24:25] op_sel_hi:[0,1]
	v_pk_mul_f32 v[20:21], v[172:173], v[20:21] op_sel_hi:[0,1]
	v_pk_mul_f32 v[26:27], v[172:173], v[26:27] op_sel_hi:[0,1]
	v_pk_mul_f32 v[22:23], v[172:173], v[22:23] op_sel_hi:[0,1]
	v_pk_mul_f32 v[32:33], v[44:45], v[32:33]
	v_pk_mul_f32 v[28:29], v[144:145], v[28:29]
	v_pk_mul_f32 v[34:35], v[46:47], v[34:35]
	v_pk_mul_f32 v[30:31], v[146:147], v[30:31]
	v_pk_mul_f32 v[24:25], v[36:37], v[24:25]
; __device__ __forceinline__ unsigned cvt_pk_bf16(float lo, float hi) { unsigned r; asm volatile("v_cvt_pk_bf16_f32 %0, %1, %2" : "=v"(r) : "v"(lo), "v"(hi)); return r; }
; __device__ __forceinline__ float fast_sigmoid(float x) { return __builtin_amdgcn_rcpf(1.0f + __expf(-x)); }
; #define PG8_BAR __builtin_amdgcn_s_barrier()
;     __device__ __forceinline__ void operator()(const i32x4 (&acc)[2][2][4][2], const Unit& u, int wr, int wc, int fr, int fq) const {
;     ...
; #pragma unroll
;         for (int ai = 0; ai < 2; ++ai)
; #pragma unroll
;             for (int m = 0; m < 4; ++m) { const int row = row0 + ai * HALF + m * 16; const float ra = rav[ai][m]; bf16_t* rowp = H + (size_t)row * ldh + col0;
;                 float hv[8];
; #pragma unroll
;                 for (int j = 0; j < 4; ++j) { const float g0 = (float)acc[ai][0][m][0][j] * ra * dg0[j], u0 = (float)acc[ai][1][m][0][j] * ra * du0[j]; hv[j] = g0 * fast_sigmoid(g0) * u0;
;                     const float g1 = (float)acc[ai][0][m][1][j] * ra * dg1[j], u1 = (float)acc[ai][1][m][1][j] * ra * du1[j]; hv[4 + j] = g1 * fast_sigmoid(g1) * u1; }
;                 u32x4 w; w.x = cvt_pk_bf16(hv[0], hv[1]); w.y = cvt_pk_bf16(hv[2], hv[3]); w.z = cvt_pk_bf16(hv[4], hv[5]); w.w = cvt_pk_bf16(hv[6], hv[7]);
;                 *(u32x4*)rowp = w; }
; template <class Epi, class Sched, bool ALIGN_EPI = false, bool SP2 = false, bool I8 = false>
; __device__ __forceinline__ void gemm_phase(PG8_LAS unsigned char* lds, const Gemm g, const Sched& S, const Epi& E) {
;     ...
;         cur = nxt; cA = nA; cB = nB; ++ui;
;         if constexpr (ALIGN_EPI) { if (wr == 1) PG8_BAR; }
	v_pk_mul_f32 v[20:21], v[140:141], v[20:21]
	v_pk_mul_f32 v[26:27], v[38:39], v[26:27]
	v_pk_mul_f32 v[22:23], v[142:143], v[22:23]
	v_pk_mul_f32 v[160:161], v[178:179], v[32:33] op_sel_hi:[0,1]
	v_pk_mul_f32 v[162:163], v[178:179], v[34:35] op_sel_hi:[0,1]
	v_exp_f32_e32 v160, v160
	v_exp_f32_e32 v161, v161
	v_exp_f32_e32 v162, v162
	v_exp_f32_e32 v163, v163
	v_pk_add_f32 v[160:161], v[178:179], v[160:161] op_sel:[1,0] op_sel_hi:[1,1]
	v_pk_add_f32 v[162:163], v[178:179], v[162:163] op_sel:[1,0] op_sel_hi:[1,1]
	v_rcp_f32_e32 v160, v160
	v_rcp_f32_e32 v161, v161
	v_rcp_f32_e32 v162, v162
	v_rcp_f32_e32 v163, v163
	v_pk_mul_f32 v[32:33], v[32:33], v[160:161]
	v_pk_mul_f32 v[34:35], v[34:35], v[162:163]
	v_pk_mul_f32 v[32:33], v[28:29], v[32:33]
	v_pk_mul_f32 v[34:35], v[30:31], v[34:35]
	v_pk_mul_f32 v[160:161], v[178:179], v[24:25] op_sel_hi:[0,1]
	v_pk_mul_f32 v[162:163], v[178:179], v[26:27] op_sel_hi:[0,1]
	v_exp_f32_e32 v160, v160
	v_exp_f32_e32 v161, v161
	v_exp_f32_e32 v162, v162
	v_exp_f32_e32 v163, v163
	v_pk_add_f32 v[160:161], v[178:179], v[160:161] op_sel:[1,0] op_sel_hi:[1,1]
	v_pk_add_f32 v[162:163], v[178:179], v[162:163] op_sel:[1,0] op_sel_hi:[1,1]
	v_rcp_f32_e32 v160, v160
	v_rcp_f32_e32 v161, v161
	v_rcp_f32_e32 v162, v162
	v_rcp_f32_e32 v163, v163
	v_pk_mul_f32 v[24:25], v[24:25], v[160:161]
	v_pk_mul_f32 v[26:27], v[26:27], v[162:163]
	v_pk_mul_f32 v[24:25], v[20:21], v[24:25]
	v_pk_mul_f32 v[26:27], v[22:23], v[26:27]
	v_cvt_pk_bf16_f32 v32, v32, v33
	v_cvt_pk_bf16_f32 v33, v34, v35
	v_cvt_pk_bf16_f32 v34, v24, v25
	v_cvt_pk_bf16_f32 v35, v26, v27
	v_add_u32_e32 v187, 0x35c000, v186
	global_store_dwordx4 v187, v[32:35], s[14:15]
	v_pk_mul_f32 v[16:17], v[172:173], v[16:17] op_sel:[1,0] op_sel_hi:[1,1]
	v_pk_mul_f32 v[12:13], v[172:173], v[12:13] op_sel:[1,0] op_sel_hi:[1,1]
	v_pk_mul_f32 v[18:19], v[172:173], v[18:19] op_sel:[1,0] op_sel_hi:[1,1]
	v_pk_mul_f32 v[14:15], v[172:173], v[14:15] op_sel:[1,0] op_sel_hi:[1,1]
	v_pk_mul_f32 v[8:9], v[172:173], v[8:9] op_sel:[1,0] op_sel_hi:[1,1]
	v_pk_mul_f32 v[4:5], v[172:173], v[4:5] op_sel:[1,0] op_sel_hi:[1,1]
	v_pk_mul_f32 v[10:11], v[172:173], v[10:11] op_sel:[1,0] op_sel_hi:[1,1]
	v_pk_mul_f32 v[6:7], v[172:173], v[6:7] op_sel:[1,0] op_sel_hi:[1,1]
	v_pk_mul_f32 v[16:17], v[44:45], v[16:17]
	v_pk_mul_f32 v[12:13], v[144:145], v[12:13]
	v_pk_mul_f32 v[18:19], v[46:47], v[18:19]
	v_pk_mul_f32 v[14:15], v[146:147], v[14:15]
	v_pk_mul_f32 v[8:9], v[36:37], v[8:9]
	v_pk_mul_f32 v[4:5], v[140:141], v[4:5]
	v_pk_mul_f32 v[10:11], v[38:39], v[10:11]
	v_pk_mul_f32 v[6:7], v[142:143], v[6:7]
	v_pk_mul_f32 v[160:161], v[178:179], v[16:17] op_sel_hi:[0,1]
	v_pk_mul_f32 v[162:163], v[178:179], v[18:19] op_sel_hi:[0,1]
	v_exp_f32_e32 v160, v160
	v_exp_f32_e32 v161, v161
	v_exp_f32_e32 v162, v162
	v_exp_f32_e32 v163, v163
	v_pk_add_f32 v[160:161], v[178:179], v[160:161] op_sel:[1,0] op_sel_hi:[1,1]
	v_pk_add_f32 v[162:163], v[178:179], v[162:163] op_sel:[1,0] op_sel_hi:[1,1]
	v_rcp_f32_e32 v160, v160
	v_rcp_f32_e32 v161, v161
	v_rcp_f32_e32 v162, v162
	v_rcp_f32_e32 v163, v163
	v_pk_mul_f32 v[16:17], v[16:17], v[160:161]
	v_pk_mul_f32 v[18:19], v[18:19], v[162:163]
	v_pk_mul_f32 v[16:17], v[12:13], v[16:17]
	v_pk_mul_f32 v[18:19], v[14:15], v[18:19]
	v_pk_mul_f32 v[160:161], v[178:179], v[8:9] op_sel_hi:[0,1]
	v_pk_mul_f32 v[162:163], v[178:179], v[10:11] op_sel_hi:[0,1]
	v_exp_f32_e32 v160, v160
	v_exp_f32_e32 v161, v161
	v_exp_f32_e32 v162, v162
	v_exp_f32_e32 v163, v163
	v_pk_add_f32 v[160:161], v[178:179], v[160:161] op_sel:[1,0] op_sel_hi:[1,1]
	v_pk_add_f32 v[162:163], v[178:179], v[162:163] op_sel:[1,0] op_sel_hi:[1,1]
	v_rcp_f32_e32 v160, v160
	v_rcp_f32_e32 v161, v161
	v_rcp_f32_e32 v162, v162
	v_rcp_f32_e32 v163, v163
	v_pk_mul_f32 v[8:9], v[8:9], v[160:161]
	v_pk_mul_f32 v[10:11], v[10:11], v[162:163]
	v_pk_mul_f32 v[8:9], v[4:5], v[8:9]
	v_pk_mul_f32 v[10:11], v[6:7], v[10:11]
	v_cvt_pk_bf16_f32 v16, v16, v17
	v_cvt_pk_bf16_f32 v17, v18, v19
	v_cvt_pk_bf16_f32 v18, v8, v9
	v_cvt_pk_bf16_f32 v19, v10, v11
	v_add_u32_e32 v187, 0x3b2000, v186
	global_store_dwordx4 v187, v[16:19], s[14:15]
	s_mov_b32 s67, 0x40000
	s_mov_b64 s[34:35], -1
	s_andn2_b64 vcc, exec, s[10:11]
	s_cbranch_vccnz .LBB0_1587
	s_andn2_b64 vcc, exec, s[12:13]
	s_cbranch_vccnz .LBB0_1586
	s_barrier
	s_branch .LBB0_1586
